# v11: grid barrier - non-leader workgroups poll the top generation word directly, per-XCD generation hop removed; on top of v10
# speedup vs baseline: 1.0437x; 1.0019x over previous
; DI unsigned xb_ld(unsigned* p)              { return __hip_atomic_load(p, __ATOMIC_RELAXED, __HIP_MEMORY_SCOPE_AGENT); }
; DI unsigned xb_add(unsigned* p, unsigned v) { return __hip_atomic_fetch_add(p, v, __ATOMIC_RELAXED, __HIP_MEMORY_SCOPE_AGENT); }
; #define XB_SPIN(cond, bar) do { unsigned _sp = 0; while (cond) { \
;     if ((++_sp & 255u) == 0u) { if (xb_ld(&(bar)[XB_TMO])) break; if (_sp > XB_SPIN_CAP) { atomicAdd(&(bar)[XB_TMO], 1u); break; } } } } while (0)
; DI void xcd_barrier(const XcdBarrier& b) {
;     ...
;     if (threadIdx.x == 0) {
;         unsigned* bar = b.bar;
;         __builtin_amdgcn_s_waitcnt(0);
;         unsigned nloc = b.st[0], nx = b.st[1];
;         if (nloc == 0u) { xcd_barrier_complete(bar, b.x, nloc, nx); b.st[0] = nloc; b.st[1] = nx; }
;         const unsigned old = xb_add(&bar[XB_XSUB(b.x)], 1u);
;         const unsigned gen = old / nloc;
;         if (old + 1u == (gen + 1u) * nloc) {
;             __builtin_amdgcn_fence(__ATOMIC_RELEASE, "agent");
;             asm volatile("s_waitcnt vmcnt(0)" ::: "memory");
;             const unsigned og = xb_add(&bar[XB_TOP], 1u);
;             const unsigned tg = og / nx;
;             if (og + 1u == (tg + 1u) * nx) xb_add(&bar[XB_TOPGEN], 1u);
;             else XB_SPIN(xb_ld(&bar[XB_TOPGEN]) == tg, bar);
;             __builtin_amdgcn_fence(__ATOMIC_ACQUIRE, "agent");
;             xb_add(&bar[XB_XGEN(b.x)], 1u);
;             asm volatile("s_waitcnt vmcnt(0)" ::: "memory");
;         } else {
;             XB_SPIN(xb_ld(&bar[XB_XGEN(b.x)]) == gen, bar);
.LBB0_143:
	s_or_b64 exec, exec, s[8:9]
	v_cvt_f32_u32_e32 v4, v2
	s_waitcnt vmcnt(0)
	v_readfirstlane_b32 s6, v3
	v_sub_u32_e32 v3, 0, v2
	v_rcp_iflag_f32_e32 v4, v4
	v_add_u32_e32 v5, s6, v1
	v_mul_f32_e32 v4, 0x4f7ffffe, v4
	v_cvt_u32_f32_e32 v4, v4
	v_mul_lo_u32 v1, v3, v4
	v_mul_hi_u32 v1, v4, v1
	v_add_u32_e32 v1, v4, v1
	v_mul_hi_u32 v1, v5, v1
	v_mul_lo_u32 v3, v1, v2
	v_sub_u32_e32 v3, v5, v3
	v_add_u32_e32 v4, 1, v1
	v_cmp_ge_u32_e32 vcc, v3, v2
	s_nop 1
	v_cndmask_b32_e32 v1, v1, v4, vcc
	v_sub_u32_e32 v4, v3, v2
	v_cndmask_b32_e32 v3, v3, v4, vcc
	v_add_u32_e32 v4, 1, v1
	v_cmp_ge_u32_e32 vcc, v3, v2
	v_add_u32_e32 v3, 1, v5
	s_nop 0
	v_cndmask_b32_e32 v1, v1, v4, vcc
	v_mul_lo_u32 v4, v2, v1
	v_add_u32_e32 v2, v4, v2
	v_cmp_ne_u32_e32 vcc, v3, v2
	s_and_saveexec_b64 s[6:7], vcc
	s_xor_b64 s[6:7], exec, s[6:7]
	s_cbranch_execz .LBB0_157
	s_waitcnt lgkmcnt(0)
	v_mov_b32_e32 v0, 0x2000
	v_mov_b32_e32 v0, 0x3000
	global_load_dword v0, v0, s[2:3] offset:1280 sc1
	s_add_u32 s10, s2, 0x3500
	s_addc_u32 s11, s3, 0
	s_waitcnt vmcnt(0)
	v_cmp_eq_u32_e32 vcc, v0, v1
	s_and_saveexec_b64 s[8:9], vcc
	s_cbranch_execz .LBB0_156
	s_mov_b32 s22, 1
	s_mov_b64 s[12:13], 0
	v_mov_b32_e32 v0, 0
	s_branch .LBB0_147

; DI unsigned xb_add(unsigned* p, unsigned v) { return __hip_atomic_fetch_add(p, v, __ATOMIC_RELAXED, __HIP_MEMORY_SCOPE_AGENT); }
; DI void xcd_barrier(const XcdBarrier& b) {
;     ...
;             __builtin_amdgcn_fence(__ATOMIC_ACQUIRE, "agent");
;             xb_add(&bar[XB_XGEN(b.x)], 1u);
;             asm volatile("s_waitcnt vmcnt(0)" ::: "memory");
.LBB0_174:
	s_or_b64 exec, exec, s[2:3]
	s_mov_b64 s[2:3], exec
	v_mbcnt_lo_u32_b32 v0, s2, 0
	v_mbcnt_hi_u32_b32 v0, s3, v0
	v_cmp_eq_u32_e32 vcc, 0, v0
	s_waitcnt vmcnt(0)
	buffer_inv sc1
	s_and_saveexec_b64 s[8:9], vcc
	s_cbranch_execz .LBB0_176
	s_bcnt1_i32_b64 s2, s[2:3]
	v_mov_b32_e32 v0, 0x2000
	v_mov_b32_e32 v1, s2
.LBB0_176:
	s_or_b64 exec, exec, s[8:9]
	s_waitcnt vmcnt(0)

; DI unsigned xb_ld(unsigned* p)              { return __hip_atomic_load(p, __ATOMIC_RELAXED, __HIP_MEMORY_SCOPE_AGENT); }
; DI unsigned xb_add(unsigned* p, unsigned v) { return __hip_atomic_fetch_add(p, v, __ATOMIC_RELAXED, __HIP_MEMORY_SCOPE_AGENT); }
; #define XB_SPIN(cond, bar) do { unsigned _sp = 0; while (cond) { \
;     if ((++_sp & 255u) == 0u) { if (xb_ld(&(bar)[XB_TMO])) break; if (_sp > XB_SPIN_CAP) { atomicAdd(&(bar)[XB_TMO], 1u); break; } } } } while (0)
; DI void xcd_barrier(const XcdBarrier& b) {
;     ...
;     if (threadIdx.x == 0) {
;         unsigned* bar = b.bar;
;         __builtin_amdgcn_s_waitcnt(0);
;         unsigned nloc = b.st[0], nx = b.st[1];
;         if (nloc == 0u) { xcd_barrier_complete(bar, b.x, nloc, nx); b.st[0] = nloc; b.st[1] = nx; }
;         const unsigned old = xb_add(&bar[XB_XSUB(b.x)], 1u);
;         const unsigned gen = old / nloc;
;         if (old + 1u == (gen + 1u) * nloc) {
;             __builtin_amdgcn_fence(__ATOMIC_RELEASE, "agent");
;             asm volatile("s_waitcnt vmcnt(0)" ::: "memory");
;             const unsigned og = xb_add(&bar[XB_TOP], 1u);
;             const unsigned tg = og / nx;
;             if (og + 1u == (tg + 1u) * nx) xb_add(&bar[XB_TOPGEN], 1u);
;             else XB_SPIN(xb_ld(&bar[XB_TOPGEN]) == tg, bar);
;             __builtin_amdgcn_fence(__ATOMIC_ACQUIRE, "agent");
;             xb_add(&bar[XB_XGEN(b.x)], 1u);
;             asm volatile("s_waitcnt vmcnt(0)" ::: "memory");
;         } else {
;             XB_SPIN(xb_ld(&bar[XB_XGEN(b.x)]) == gen, bar);
.LBB0_245:
	s_or_b64 exec, exec, s[10:11]
	v_cvt_f32_u32_e32 v4, v2
	s_waitcnt vmcnt(0)
	v_readfirstlane_b32 s0, v3
	v_sub_u32_e32 v3, 0, v2
	v_rcp_iflag_f32_e32 v4, v4
	v_add_u32_e32 v5, s0, v1
	v_mul_f32_e32 v4, 0x4f7ffffe, v4
	v_cvt_u32_f32_e32 v4, v4
	v_mul_lo_u32 v1, v3, v4
	v_mul_hi_u32 v1, v4, v1
	v_add_u32_e32 v1, v4, v1
	v_mul_hi_u32 v1, v5, v1
	v_mul_lo_u32 v3, v1, v2
	v_sub_u32_e32 v3, v5, v3
	v_add_u32_e32 v4, 1, v1
	v_cmp_ge_u32_e32 vcc, v3, v2
	s_nop 1
	v_cndmask_b32_e32 v1, v1, v4, vcc
	v_sub_u32_e32 v4, v3, v2
	v_cndmask_b32_e32 v3, v3, v4, vcc
	v_add_u32_e32 v4, 1, v1
	v_cmp_ge_u32_e32 vcc, v3, v2
	v_add_u32_e32 v3, 1, v5
	s_nop 0
	v_cndmask_b32_e32 v1, v1, v4, vcc
	v_mul_lo_u32 v4, v2, v1
	v_add_u32_e32 v2, v4, v2
	v_cmp_ne_u32_e32 vcc, v3, v2
	s_and_saveexec_b64 s[8:9], vcc
	s_xor_b64 s[8:9], exec, s[8:9]
	s_cbranch_execz .LBB0_259
	s_waitcnt lgkmcnt(0)
	v_mov_b32_e32 v0, 0x3000
	global_load_dword v0, v0, s[4:5] offset:1280 sc1
	s_add_u32 s12, s4, 0x3500
	s_addc_u32 s13, s5, 0
	s_waitcnt vmcnt(0)
	v_cmp_eq_u32_e32 vcc, v0, v1
	s_and_saveexec_b64 s[10:11], vcc
	s_cbranch_execz .LBB0_258
	s_mov_b32 s0, 1
	s_mov_b64 s[14:15], 0
	s_branch .LBB0_249

; DI unsigned xb_add(unsigned* p, unsigned v) { return __hip_atomic_fetch_add(p, v, __ATOMIC_RELAXED, __HIP_MEMORY_SCOPE_AGENT); }
; DI void xcd_barrier(const XcdBarrier& b) {
;     ...
;             __builtin_amdgcn_fence(__ATOMIC_ACQUIRE, "agent");
;             xb_add(&bar[XB_XGEN(b.x)], 1u);
;             asm volatile("s_waitcnt vmcnt(0)" ::: "memory");
.LBB0_276:
	s_or_b64 exec, exec, s[4:5]
	s_mov_b64 s[4:5], exec
	v_mbcnt_lo_u32_b32 v0, s4, 0
	v_mbcnt_hi_u32_b32 v0, s5, v0
	v_cmp_eq_u32_e32 vcc, 0, v0
	s_waitcnt vmcnt(0)
	buffer_inv sc1
	s_and_saveexec_b64 s[10:11], vcc
	s_cbranch_execz .LBB0_278
	s_bcnt1_i32_b64 s0, s[4:5]
	v_mov_b32_e32 v0, s0
.LBB0_278:
	s_or_b64 exec, exec, s[10:11]
	s_waitcnt vmcnt(0)

; DI unsigned xb_add(unsigned* p, unsigned v) { return __hip_atomic_fetch_add(p, v, __ATOMIC_RELAXED, __HIP_MEMORY_SCOPE_AGENT); }
; DI void xcd_barrier(const XcdBarrier& b) {
;     ...
;             __builtin_amdgcn_fence(__ATOMIC_ACQUIRE, "agent");
;             xb_add(&bar[XB_XGEN(b.x)], 1u);
;             asm volatile("s_waitcnt vmcnt(0)" ::: "memory");
.LBB0_350:
	s_or_b64 exec, exec, s[4:5]
	s_mov_b64 s[4:5], exec
	v_mbcnt_lo_u32_b32 v0, s4, 0
	v_mbcnt_hi_u32_b32 v0, s5, v0
	v_cmp_eq_u32_e32 vcc, 0, v0
	s_waitcnt vmcnt(0)
	buffer_inv sc1
	s_and_saveexec_b64 s[8:9], vcc
	s_cbranch_execz .LBB0_352
	s_bcnt1_i32_b64 s0, s[4:5]
	v_mov_b32_e32 v0, s0
.LBB0_352:
	s_or_b64 exec, exec, s[8:9]
	s_waitcnt vmcnt(0)

; DI unsigned xb_add(unsigned* p, unsigned v) { return __hip_atomic_fetch_add(p, v, __ATOMIC_RELAXED, __HIP_MEMORY_SCOPE_AGENT); }
; DI void xcd_barrier(const XcdBarrier& b) {
;     ...
;             __builtin_amdgcn_fence(__ATOMIC_ACQUIRE, "agent");
;             xb_add(&bar[XB_XGEN(b.x)], 1u);
;             asm volatile("s_waitcnt vmcnt(0)" ::: "memory");
.LBB0_527:
	s_or_b64 exec, exec, s[4:5]
	s_mov_b64 s[4:5], exec
	v_mbcnt_lo_u32_b32 v0, s4, 0
	v_mbcnt_hi_u32_b32 v0, s5, v0
	v_cmp_eq_u32_e32 vcc, 0, v0
	s_waitcnt vmcnt(0)
	buffer_inv sc1
	s_and_saveexec_b64 s[8:9], vcc
	s_cbranch_execz .LBB0_529
	s_bcnt1_i32_b64 s0, s[4:5]
	v_mov_b32_e32 v0, s0
.LBB0_529:
	s_or_b64 exec, exec, s[8:9]
	s_waitcnt vmcnt(0)

; DI unsigned xb_add(unsigned* p, unsigned v) { return __hip_atomic_fetch_add(p, v, __ATOMIC_RELAXED, __HIP_MEMORY_SCOPE_AGENT); }
; DI void xcd_barrier(const XcdBarrier& b) {
;     ...
;             __builtin_amdgcn_fence(__ATOMIC_ACQUIRE, "agent");
;             xb_add(&bar[XB_XGEN(b.x)], 1u);
;             asm volatile("s_waitcnt vmcnt(0)" ::: "memory");
.LBB0_595:
	s_or_b64 exec, exec, s[4:5]
	s_mov_b64 s[4:5], exec
	v_mbcnt_lo_u32_b32 v0, s4, 0
	v_mbcnt_hi_u32_b32 v0, s5, v0
	v_cmp_eq_u32_e32 vcc, 0, v0
	s_waitcnt vmcnt(0)
	buffer_inv sc1
	s_and_saveexec_b64 s[8:9], vcc
	s_cbranch_execz .LBB0_597
	s_bcnt1_i32_b64 s0, s[4:5]
	v_mov_b32_e32 v0, s0
.LBB0_597:
	s_or_b64 exec, exec, s[8:9]
	s_waitcnt vmcnt(0)

; DI unsigned xb_add(unsigned* p, unsigned v) { return __hip_atomic_fetch_add(p, v, __ATOMIC_RELAXED, __HIP_MEMORY_SCOPE_AGENT); }
; DI void xcd_barrier(const XcdBarrier& b) {
;     ...
;             __builtin_amdgcn_fence(__ATOMIC_ACQUIRE, "agent");
;             xb_add(&bar[XB_XGEN(b.x)], 1u);
;             asm volatile("s_waitcnt vmcnt(0)" ::: "memory");
.LBB0_725:
	s_or_b64 exec, exec, s[4:5]
	s_mov_b64 s[4:5], exec
	v_mbcnt_lo_u32_b32 v0, s4, 0
	v_mbcnt_hi_u32_b32 v0, s5, v0
	v_cmp_eq_u32_e32 vcc, 0, v0
	s_waitcnt vmcnt(0)
	buffer_inv sc1
	s_and_saveexec_b64 s[8:9], vcc
	s_cbranch_execz .LBB0_727
	s_bcnt1_i32_b64 s0, s[4:5]
	v_mov_b32_e32 v0, s0
.LBB0_727:
	s_or_b64 exec, exec, s[8:9]
	s_waitcnt vmcnt(0)

; DI unsigned xb_add(unsigned* p, unsigned v) { return __hip_atomic_fetch_add(p, v, __ATOMIC_RELAXED, __HIP_MEMORY_SCOPE_AGENT); }
; DI void xcd_barrier(const XcdBarrier& b) {
;     ...
;             __builtin_amdgcn_fence(__ATOMIC_ACQUIRE, "agent");
;             xb_add(&bar[XB_XGEN(b.x)], 1u);
;             asm volatile("s_waitcnt vmcnt(0)" ::: "memory");
.LBB0_785:
	s_or_b64 exec, exec, s[4:5]
	s_mov_b64 s[4:5], exec
	v_mbcnt_lo_u32_b32 v0, s4, 0
	v_mbcnt_hi_u32_b32 v0, s5, v0
	v_cmp_eq_u32_e32 vcc, 0, v0
	s_waitcnt vmcnt(0)
	buffer_inv sc1
	s_and_saveexec_b64 s[8:9], vcc
	s_cbranch_execz .LBB0_787
	s_bcnt1_i32_b64 s0, s[4:5]
	v_mov_b32_e32 v0, s0
.LBB0_787:
	s_or_b64 exec, exec, s[8:9]
	s_waitcnt vmcnt(0)

; DI unsigned xb_add(unsigned* p, unsigned v) { return __hip_atomic_fetch_add(p, v, __ATOMIC_RELAXED, __HIP_MEMORY_SCOPE_AGENT); }
; DI void xcd_barrier(const XcdBarrier& b) {
;     ...
;             __builtin_amdgcn_fence(__ATOMIC_ACQUIRE, "agent");
;             xb_add(&bar[XB_XGEN(b.x)], 1u);
;             asm volatile("s_waitcnt vmcnt(0)" ::: "memory");
.LBB0_1106:
	s_or_b64 exec, exec, s[4:5]
	s_mov_b64 s[4:5], exec
	v_mbcnt_lo_u32_b32 v0, s4, 0
	v_mbcnt_hi_u32_b32 v0, s5, v0
	v_cmp_eq_u32_e32 vcc, 0, v0
	s_waitcnt vmcnt(0)
	buffer_inv sc1
	s_and_saveexec_b64 s[8:9], vcc
	s_cbranch_execz .LBB0_1108
	s_bcnt1_i32_b64 s0, s[4:5]
	v_mov_b32_e32 v0, s0
.LBB0_1108:
	s_or_b64 exec, exec, s[8:9]
	s_waitcnt vmcnt(0)

; DI unsigned xb_ld(unsigned* p)              { return __hip_atomic_load(p, __ATOMIC_RELAXED, __HIP_MEMORY_SCOPE_AGENT); }
; DI unsigned xb_add(unsigned* p, unsigned v) { return __hip_atomic_fetch_add(p, v, __ATOMIC_RELAXED, __HIP_MEMORY_SCOPE_AGENT); }
; #define XB_SPIN(cond, bar) do { unsigned _sp = 0; while (cond) { \
;     if ((++_sp & 255u) == 0u) { if (xb_ld(&(bar)[XB_TMO])) break; if (_sp > XB_SPIN_CAP) { atomicAdd(&(bar)[XB_TMO], 1u); break; } } } } while (0)
; DI void xcd_barrier(const XcdBarrier& b) {
;     ...
;     if (threadIdx.x == 0) {
;         unsigned* bar = b.bar;
;         __builtin_amdgcn_s_waitcnt(0);
;         unsigned nloc = b.st[0], nx = b.st[1];
;         if (nloc == 0u) { xcd_barrier_complete(bar, b.x, nloc, nx); b.st[0] = nloc; b.st[1] = nx; }
;         const unsigned old = xb_add(&bar[XB_XSUB(b.x)], 1u);
;         const unsigned gen = old / nloc;
;         if (old + 1u == (gen + 1u) * nloc) {
;             __builtin_amdgcn_fence(__ATOMIC_RELEASE, "agent");
;             asm volatile("s_waitcnt vmcnt(0)" ::: "memory");
;             const unsigned og = xb_add(&bar[XB_TOP], 1u);
;             const unsigned tg = og / nx;
;             if (og + 1u == (tg + 1u) * nx) xb_add(&bar[XB_TOPGEN], 1u);
;             else XB_SPIN(xb_ld(&bar[XB_TOPGEN]) == tg, bar);
;             __builtin_amdgcn_fence(__ATOMIC_ACQUIRE, "agent");
;             xb_add(&bar[XB_XGEN(b.x)], 1u);
;             asm volatile("s_waitcnt vmcnt(0)" ::: "memory");
;         } else {
;             XB_SPIN(xb_ld(&bar[XB_XGEN(b.x)]) == gen, bar);
.LBB0_1248:
	s_or_b64 exec, exec, s[12:13]
	v_cvt_f32_u32_e32 v4, v2
	s_waitcnt vmcnt(0)
	v_readfirstlane_b32 s0, v3
	v_sub_u32_e32 v3, 0, v2
	v_rcp_iflag_f32_e32 v4, v4
	v_add_u32_e32 v5, s0, v1
	v_mul_f32_e32 v4, 0x4f7ffffe, v4
	v_cvt_u32_f32_e32 v4, v4
	v_mul_lo_u32 v1, v3, v4
	v_mul_hi_u32 v1, v4, v1
	v_add_u32_e32 v1, v4, v1
	v_mul_hi_u32 v1, v5, v1
	v_mul_lo_u32 v3, v1, v2
	v_sub_u32_e32 v3, v5, v3
	v_add_u32_e32 v4, 1, v1
	v_cmp_ge_u32_e32 vcc, v3, v2
	s_nop 1
	v_cndmask_b32_e32 v1, v1, v4, vcc
	v_sub_u32_e32 v4, v3, v2
	v_cndmask_b32_e32 v3, v3, v4, vcc
	v_add_u32_e32 v4, 1, v1
	v_cmp_ge_u32_e32 vcc, v3, v2
	v_add_u32_e32 v3, 1, v5
	s_nop 0
	v_cndmask_b32_e32 v1, v1, v4, vcc
	v_mul_lo_u32 v4, v2, v1
	v_add_u32_e32 v2, v4, v2
	v_cmp_ne_u32_e32 vcc, v3, v2
	s_and_saveexec_b64 s[10:11], vcc
	s_xor_b64 s[10:11], exec, s[10:11]
	s_cbranch_execz .LBB0_1262
	s_waitcnt lgkmcnt(0)
	v_mov_b32_e32 v0, 0x3000
	global_load_dword v0, v0, s[4:5] offset:1280 sc1
	s_add_u32 s14, s4, 0x3500
	s_addc_u32 s15, s5, 0
	s_waitcnt vmcnt(0)
	v_cmp_eq_u32_e32 vcc, v0, v1
	s_and_saveexec_b64 s[12:13], vcc
	s_cbranch_execz .LBB0_1261
	s_mov_b32 s0, 1
	s_mov_b64 s[16:17], 0
	s_branch .LBB0_1252

; DI unsigned xb_add(unsigned* p, unsigned v) { return __hip_atomic_fetch_add(p, v, __ATOMIC_RELAXED, __HIP_MEMORY_SCOPE_AGENT); }
; DI void xcd_barrier(const XcdBarrier& b) {
;     ...
;             __builtin_amdgcn_fence(__ATOMIC_ACQUIRE, "agent");
;             xb_add(&bar[XB_XGEN(b.x)], 1u);
;             asm volatile("s_waitcnt vmcnt(0)" ::: "memory");
.LBB0_1279:
	s_or_b64 exec, exec, s[4:5]
	s_mov_b64 s[4:5], exec
	v_mbcnt_lo_u32_b32 v0, s4, 0
	v_mbcnt_hi_u32_b32 v0, s5, v0
	v_cmp_eq_u32_e32 vcc, 0, v0
	s_waitcnt vmcnt(0)
	buffer_inv sc1
	s_and_saveexec_b64 s[10:11], vcc
	s_cbranch_execz .LBB0_1281
	s_bcnt1_i32_b64 s0, s[4:5]
	v_mov_b32_e32 v0, s0
.LBB0_1281:
	s_or_b64 exec, exec, s[10:11]
	s_waitcnt vmcnt(0)

; DI unsigned xb_add(unsigned* p, unsigned v) { return __hip_atomic_fetch_add(p, v, __ATOMIC_RELAXED, __HIP_MEMORY_SCOPE_AGENT); }
; DI void xcd_barrier(const XcdBarrier& b) {
;     ...
;             __builtin_amdgcn_fence(__ATOMIC_ACQUIRE, "agent");
;             xb_add(&bar[XB_XGEN(b.x)], 1u);
;             asm volatile("s_waitcnt vmcnt(0)" ::: "memory");
.LBB0_1351:
	s_or_b64 exec, exec, s[4:5]
	s_mov_b64 s[4:5], exec
	v_mbcnt_lo_u32_b32 v0, s4, 0
	v_mbcnt_hi_u32_b32 v0, s5, v0
	v_cmp_eq_u32_e32 vcc, 0, v0
	s_waitcnt vmcnt(0)
	buffer_inv sc1
	s_and_saveexec_b64 s[10:11], vcc
	s_cbranch_execz .LBB0_1353
	s_bcnt1_i32_b64 s0, s[4:5]
	v_mov_b32_e32 v0, s0
.LBB0_1353:
	s_or_b64 exec, exec, s[10:11]
	s_waitcnt vmcnt(0)

; DI unsigned xb_add(unsigned* p, unsigned v) { return __hip_atomic_fetch_add(p, v, __ATOMIC_RELAXED, __HIP_MEMORY_SCOPE_AGENT); }
; DI void xcd_barrier(const XcdBarrier& b) {
;     ...
;             __builtin_amdgcn_fence(__ATOMIC_ACQUIRE, "agent");
;             xb_add(&bar[XB_XGEN(b.x)], 1u);
;             asm volatile("s_waitcnt vmcnt(0)" ::: "memory");
.LBB0_1529:
	s_bcnt1_i32_b64 s0, s[4:5]
	v_mov_b32_e32 v0, s0
	s_getpc_b64 s[98:99]
